# layer-0 W2 conversion moved to the 128 idle WGs of the out-projection's second round (site 6); P1(l0) skips W2 tiles
# speedup vs baseline: 1.0030x; 1.0030x over previous
; #define WT_LOAD() do { _Pragma("unroll") for (int i = 0; i < 16; ++i) rg[i] = sp ? sp[(size_t)(k0 + kq + i * 8) * ld] : 0.f; } while (0)
; __device__ __forceinline__ void phase_weights(int wv, const Params& p, int l, LAS unsigned char* lds, int first, int stride) {
;     ...
;     while (ti < 1536) {
;         bf16_t* cdst = dst + (size_t)n0 * K + k0; const int cK = K;
;         __syncthreads();
; #pragma unroll
;         for (int i = 0; i < 16; ++i) tile[(kq + i * 8) * 65 + nl] = rg[i];
;         ti += stride;
;         if (ti < 1536) { WT_DECODE(ti); WT_LOAD(); }
.LBB0_232:
	s_add_i32 s46, s46, s1
	s_cmpk_lg_u32 s44, 0x100
	s_cbranch_scc1 .Lws_done
	v_readlane_b32 s101, v255, 22
	s_cmp_eq_u32 s101, 1
	s_cbranch_scc1 .Lws_loop
	s_cmpk_lt_i32 s46, 0x4a0
	s_cbranch_scc1 .Lws_done
	s_movk_i32 s46, 0x600
	s_branch .Lws_done

; __device__ __forceinline__ unsigned pk_bf16(float lo, float hi) { unsigned r; asm volatile("v_cvt_pk_bf16_f32 %0, %1, %2" : "=v"(r) : "v"(lo), "v"(hi)); return r; }
; #define WT_LOAD() do { _Pragma("unroll") for (int i = 0; i < 16; ++i) rg[i] = sp ? sp[(size_t)(k0 + kq + i * 8) * ld] : 0.f; } while (0)
; __device__ __forceinline__ void phase_weights(int wv, const Params& p, int l, LAS unsigned char* lds, int first, int stride) {
;     ...
;     if (ti < 1536) { WT_DECODE(ti); WT_LOAD(); }
;     while (ti < 1536) {
;         bf16_t* cdst = dst + (size_t)n0 * K + k0; const int cK = K;
;         __syncthreads();
; #pragma unroll
;         for (int i = 0; i < 16; ++i) tile[(kq + i * 8) * 65 + nl] = rg[i];
;         ti += stride;
;         if (ti < 1536) { WT_DECODE(ti); WT_LOAD(); }
;         __syncthreads();
;         { const int nn = tid >> 3, ks = tid & 7; float v[16];
; #pragma unroll
;             for (int j = 0; j < 16; ++j) v[j] = tile[(ks * 16 + j) * 65 + nn];
;             u32x4 w0, w1; w0.x = pk_bf16(v[0], v[1]); w0.y = pk_bf16(v[2], v[3]); w0.z = pk_bf16(v[4], v[5]); w0.w = pk_bf16(v[6], v[7]);
;             w1.x = pk_bf16(v[8], v[9]); w1.y = pk_bf16(v[10], v[11]); w1.z = pk_bf16(v[12], v[13]); w1.w = pk_bf16(v[14], v[15]);
;             bf16_t* o = cdst + (size_t)nn * cK + ks * 16; *(u32x4*)o = w0; *(u32x4*)(o + 8) = w1; }
.LBB0_1163:
	v_writelane_b32 v255, s24, 63
	v_readlane_b32 s24, v255, 3
	s_cmpk_lt_u32 s24, 128
	s_cbranch_scc1 .Lew_end_a
	s_cmpk_lg_u32 s44, 0x100
	s_cbranch_scc1 .Lew_end_a
	v_readlane_b32 s24, v255, 22
	s_cmp_lg_u32 s24, 0
	s_cbranch_scc1 .Lew_end_a
	v_writelane_b32 v255, s3, 43
	v_writelane_b32 v255, s6, 44
	v_writelane_b32 v255, s7, 45
	v_writelane_b32 v255, s14, 46
	v_writelane_b32 v255, s15, 47
	v_writelane_b32 v255, s16, 48
	v_writelane_b32 v255, s17, 49
	v_writelane_b32 v255, s18, 50
	v_writelane_b32 v255, s19, 51
	v_writelane_b32 v255, s22, 52
	v_writelane_b32 v255, s23, 53
	v_writelane_b32 v255, s26, 54
	v_writelane_b32 v255, s27, 55
	v_writelane_b32 v255, s30, 56
	v_writelane_b32 v255, s31, 57
	v_writelane_b32 v255, s36, 58
	v_writelane_b32 v255, s37, 59
	s_load_dwordx2 s[14:15], s[90:91], 0x98
	s_load_dwordx2 s[16:17], s[90:91], 0xa8
	v_mbcnt_lo_u32_b32 v2, -1, 0
	v_mbcnt_hi_u32_b32 v2, -1, v2
	v_and_b32_e32 v3, 15, v2
	v_lshrrev_b32_e32 v6, 4, v2
	v_lshlrev_b32_e32 v12, 4, v3
	v_lshl_add_u32 v12, v6, 16, v12
	v_mov_b32_e32 v13, 0
	v_mul_u32_u24_e32 v10, 0x5800, v3
	v_lshl_add_u32 v10, v6, 5, v10
	s_waitcnt lgkmcnt(0)
	v_mov_b32_e32 v4, s14
	v_mov_b32_e32 v5, s15
	v_lshl_add_u64 v[4:5], v[4:5], 0, v[12:13]
	s_add_u32 s16, s16, 0xc04c000
	s_addc_u32 s17, s17, 0
	v_readlane_b32 s24, v255, 7
	s_lshr_b32 s24, s24, 6
	v_readlane_b32 s3, v255, 3
	s_sub_i32 s3, s3, 128
	s_lshl_b32 s3, s3, 3
	s_add_i32 s3, s3, s24
.Lew_loop_a:
	s_cmpk_gt_u32 s3, 0x2bf
	s_cbranch_scc1 .Lew_rest_a
	s_mul_hi_u32 s6, s3, 0x5d1745e
	s_mul_i32 s7, s6, 44
	s_sub_i32 s7, s3, s7
	s_lshl_b32 s22, s7, 18
	s_lshl_b32 s24, s6, 8
	s_add_i32 s22, s22, s24
	s_mov_b32 s23, 0
	s_mul_i32 s24, s6, 0x58000
	s_lshl_b32 s7, s7, 7
	s_add_i32 s24, s24, s7
	s_add_u32 s18, s16, s24
	s_addc_u32 s19, s17, 0
	s_add_u32 s26, s18, 0x1600
	s_addc_u32 s27, s19, 0
	s_add_u32 s30, s26, 0x1600
	s_addc_u32 s31, s27, 0
	s_add_u32 s36, s30, 0x1600
	s_addc_u32 s37, s31, 0
	v_lshl_add_u64 v[6:7], s[22:23], 0, v[4:5]
	global_load_dwordx4 v[20:23], v[6:7], off
	s_add_u32 s22, s22, 0x1000
	v_lshl_add_u64 v[8:9], s[22:23], 0, v[4:5]
	global_load_dwordx4 v[24:27], v[8:9], off
	s_add_u32 s22, s22, 0x1000
	v_lshl_add_u64 v[6:7], s[22:23], 0, v[4:5]
	global_load_dwordx4 v[28:31], v[6:7], off
	s_add_u32 s22, s22, 0x1000
	v_lshl_add_u64 v[8:9], s[22:23], 0, v[4:5]
	global_load_dwordx4 v[32:35], v[8:9], off
	s_add_u32 s22, s22, 0x1000
	v_lshl_add_u64 v[6:7], s[22:23], 0, v[4:5]
	global_load_dwordx4 v[36:39], v[6:7], off
	s_add_u32 s22, s22, 0x1000
	v_lshl_add_u64 v[8:9], s[22:23], 0, v[4:5]
	global_load_dwordx4 v[40:43], v[8:9], off
	s_add_u32 s22, s22, 0x1000
	v_lshl_add_u64 v[6:7], s[22:23], 0, v[4:5]
	global_load_dwordx4 v[44:47], v[6:7], off
	s_add_u32 s22, s22, 0x1000
	v_lshl_add_u64 v[8:9], s[22:23], 0, v[4:5]
	global_load_dwordx4 v[48:51], v[8:9], off
	s_add_u32 s22, s22, 0x1000
	v_lshl_add_u64 v[6:7], s[22:23], 0, v[4:5]
	global_load_dwordx4 v[52:55], v[6:7], off
	s_add_u32 s22, s22, 0x1000
	v_lshl_add_u64 v[8:9], s[22:23], 0, v[4:5]
	global_load_dwordx4 v[56:59], v[8:9], off
	s_add_u32 s22, s22, 0x1000
	v_lshl_add_u64 v[6:7], s[22:23], 0, v[4:5]
	global_load_dwordx4 v[60:63], v[6:7], off
	s_add_u32 s22, s22, 0x1000
	v_lshl_add_u64 v[8:9], s[22:23], 0, v[4:5]
	global_load_dwordx4 v[64:67], v[8:9], off
	s_add_u32 s22, s22, 0x1000
	v_lshl_add_u64 v[6:7], s[22:23], 0, v[4:5]
	global_load_dwordx4 v[68:71], v[6:7], off
	s_add_u32 s22, s22, 0x1000
	v_lshl_add_u64 v[8:9], s[22:23], 0, v[4:5]
	global_load_dwordx4 v[72:75], v[8:9], off
	s_add_u32 s22, s22, 0x1000
	v_lshl_add_u64 v[6:7], s[22:23], 0, v[4:5]
	global_load_dwordx4 v[76:79], v[6:7], off
	s_add_u32 s22, s22, 0x1000
	v_lshl_add_u64 v[8:9], s[22:23], 0, v[4:5]
	global_load_dwordx4 v[80:83], v[8:9], off
	s_add_u32 s22, s22, 0x1000
	s_waitcnt vmcnt(0)
	v_cvt_pk_bf16_f32 v84, v20, v24
	v_cvt_pk_bf16_f32 v85, v28, v32
	v_cvt_pk_bf16_f32 v86, v36, v40
	v_cvt_pk_bf16_f32 v87, v44, v48
	v_cvt_pk_bf16_f32 v88, v52, v56
	v_cvt_pk_bf16_f32 v89, v60, v64
	v_cvt_pk_bf16_f32 v90, v68, v72
	v_cvt_pk_bf16_f32 v91, v76, v80
	v_cvt_pk_bf16_f32 v92, v21, v25
	v_cvt_pk_bf16_f32 v93, v29, v33
	v_cvt_pk_bf16_f32 v94, v37, v41
	v_cvt_pk_bf16_f32 v95, v45, v49
	v_cvt_pk_bf16_f32 v96, v53, v57
	v_cvt_pk_bf16_f32 v97, v61, v65
	v_cvt_pk_bf16_f32 v98, v69, v73
	v_cvt_pk_bf16_f32 v99, v77, v81
	v_cvt_pk_bf16_f32 v100, v22, v26
	v_cvt_pk_bf16_f32 v101, v30, v34
	v_cvt_pk_bf16_f32 v102, v38, v42
	v_cvt_pk_bf16_f32 v103, v46, v50
	v_cvt_pk_bf16_f32 v104, v54, v58
	v_cvt_pk_bf16_f32 v105, v62, v66
	v_cvt_pk_bf16_f32 v106, v70, v74
	v_cvt_pk_bf16_f32 v107, v78, v82
	v_cvt_pk_bf16_f32 v108, v23, v27
	v_cvt_pk_bf16_f32 v109, v31, v35
	v_cvt_pk_bf16_f32 v110, v39, v43
	v_cvt_pk_bf16_f32 v111, v47, v51
	v_cvt_pk_bf16_f32 v112, v55, v59
	v_cvt_pk_bf16_f32 v113, v63, v67
	v_cvt_pk_bf16_f32 v114, v71, v75
	v_cvt_pk_bf16_f32 v115, v79, v83
	global_store_dwordx4 v10, v[84:87], s[18:19]
	global_store_dwordx4 v10, v[88:91], s[18:19] offset:16
	global_store_dwordx4 v10, v[92:95], s[26:27]
	global_store_dwordx4 v10, v[96:99], s[26:27] offset:16
	global_store_dwordx4 v10, v[100:103], s[30:31]
	global_store_dwordx4 v10, v[104:107], s[30:31] offset:16
	global_store_dwordx4 v10, v[108:111], s[36:37]
	global_store_dwordx4 v10, v[112:115], s[36:37] offset:16
	s_addk_i32 s3, 0x400
	s_branch .Lew_loop_a
; #define LAS __attribute__((address_space(3)))
; __device__ __forceinline__ int otid(int wv) { int ln; asm volatile("v_mbcnt_lo_u32_b32 %0, -1, 0\n\tv_mbcnt_hi_u32_b32 %0, -1, %0" : "=v"(ln)); return wv * 64 + ln; }
; __device__ __forceinline__ unsigned xb_xcc_id() { return (unsigned)__builtin_amdgcn_s_getreg((3 << 11) | 20) & 0xFu; }
; __device__ __forceinline__ void grid_bar(int wv, unsigned* bar, volatile LAS unsigned* st) {
;     asm volatile("s_waitcnt vmcnt(0)" ::: "memory");
;     __syncthreads();
;     if (otid(wv) == 0) {
;         __builtin_amdgcn_s_waitcnt(0);
;         const unsigned x = xb_xcc_id();
;         unsigned nloc = st[0], nx = st[1];
;         if (nloc == 0u) { xcd_barrier_complete(bar, x, nloc, nx); st[0] = nloc; st[1] = nx; }
.Lew_rest_a:
	v_readlane_b32 s3, v255, 43
	v_readlane_b32 s6, v255, 44
	v_readlane_b32 s7, v255, 45
	v_readlane_b32 s14, v255, 46
	v_readlane_b32 s15, v255, 47
	v_readlane_b32 s16, v255, 48
	v_readlane_b32 s17, v255, 49
	v_readlane_b32 s18, v255, 50
	v_readlane_b32 s19, v255, 51
	v_readlane_b32 s22, v255, 52
	v_readlane_b32 s23, v255, 53
	v_readlane_b32 s26, v255, 54
	v_readlane_b32 s27, v255, 55
	v_readlane_b32 s30, v255, 56
	v_readlane_b32 s31, v255, 57
	v_readlane_b32 s36, v255, 58
	v_readlane_b32 s37, v255, 59
.Lew_end_a:
	v_readlane_b32 s24, v255, 63
	s_mov_b64 s[4:5], s[90:91]
	s_waitcnt vmcnt(0)
	v_readlane_b32 s0, v253, 3
	s_waitcnt vmcnt(0) lgkmcnt(0)
	s_barrier
	v_mbcnt_lo_u32_b32 v0, -1, 0
	v_mbcnt_hi_u32_b32 v0, -1, v0
	s_nop 0
	v_cmp_eq_u32_e32 vcc, s0, v0
	s_and_saveexec_b64 s[6:7], vcc
	v_readlane_b32 s38, v255, 10
	v_readlane_b32 s96, v255, 3
	v_readlane_b32 s39, v255, 11
	v_readlane_b32 s40, v255, 12
	v_readlane_b32 s97, v255, 4
	v_readlane_b32 s41, v255, 13
	s_movk_i32 s42, 0x6000
	s_movk_i32 s39, 0x4000
	s_mov_b32 s94, 0x3a800000
	s_mov_b64 s[72:73], 0x3000
	s_mov_b64 s[74:75], 0x4000
	s_cbranch_execz .LBB0_1215
	v_readlane_b32 s1, v254, 63
	s_load_dwordx2 s[8:9], s[4:5], 0xa8
	s_waitcnt vmcnt(0) expcnt(0) lgkmcnt(0)
	v_mov_b32_e32 v0, s1
	s_getreg_b32 s0, hwreg(HW_REG_XCC_ID, 0, 4)
	ds_read_b32 v3, v0
	v_readlane_b32 s1, v255, 0
	s_and_b32 s0, s0, 15
	s_waitcnt lgkmcnt(0)
	v_cmp_ne_u32_e32 vcc, 0, v3
	v_mov_b32_e32 v0, s1
	ds_read_b32 v2, v0
	s_cbranch_vccnz .LBB0_1179
	s_add_u32 s14, s8, 0xfab9b00
	s_addc_u32 s15, s9, 0
	s_add_u32 s16, s8, 0xfab9d00
	s_addc_u32 s17, s9, 0
	s_add_u32 s18, s8, 0xfab9e00
	s_addc_u32 s19, s9, 0
	s_add_u32 s22, s8, 0xfab9f00
	s_addc_u32 s23, s9, 0
	s_add_u32 s24, s8, 0xfaba000
	s_addc_u32 s25, s9, 0
	s_add_u32 s26, s8, 0xfaba100
	s_addc_u32 s27, s9, 0
	s_add_u32 s30, s8, 0xfaba200
	s_addc_u32 s31, s9, 0
	s_add_u32 s34, s8, 0xfaba300
	s_addc_u32 s35, s9, 0
	s_add_u32 s36, s8, 0xfaba400
	s_addc_u32 s37, s9, 0
	s_add_u32 s38, s8, 0xfaba500
	s_addc_u32 s39, s9, 0
	s_add_u32 s40, s8, 0xfaba600
	s_addc_u32 s41, s9, 0
	s_add_u32 s42, s8, 0xfaba700
	s_addc_u32 s43, s9, 0
	s_add_u32 s48, s8, 0xfaba800
	s_addc_u32 s49, s9, 0
	s_add_u32 s50, s8, 0xfaba900
	s_addc_u32 s51, s9, 0
	s_add_u32 s52, s8, 0xfabaa00
	s_addc_u32 s53, s9, 0
	s_add_u32 s60, s8, 0xfabab00
	s_addc_u32 s61, s9, 0
	s_add_u32 s64, s8, 0xfabac00
	s_addc_u32 s65, s9, 0
	s_mov_b32 s1, 1
	s_branch .LBB0_1167
